# scan pass 1: the wave that runs the triangular solve gets raised priority from the solve until the stage barrier (it is the critical wave of that stage)
# speedup vs baseline: 1.0102x; 1.0040x over previous
; #define LAS __attribute__((address_space(3)))
; __device__ __forceinline__ void scan_pass1(const ScanP& sp, int b, int h, int seg, LAS unsigned char* lds) {
;     ...
;             if (job == 1) {
; #pragma unroll
;                 for (int r = 0; r < 16; ++r) { const int c = crow(r, hh); NT[c * 32 + ln] = (c < ln) ? Z[r] : 0.f; }
;                 {
;                     const bool lowrow = ln < 16;
;                     u32x2 a_, b_;
;                     a_.x = lowrow ? 0u : pk2(-Z[0], -Z[1]); a_.y = lowrow ? 0u : pk2(-Z[2], -Z[3]);
;                     b_.x = lowrow ? 0u : pk2(-Z[4], -Z[5]); b_.y = lowrow ? 0u : pk2(-Z[6], -Z[7]);
;                     *(LAS u32x2*)(lds + O_N21 + (ln * 40 + 4 * hh) * 2) = a_;
;                     *(LAS u32x2*)(lds + O_N21 + (ln * 40 + 8 + 4 * hh) * 2) = b_;
;                 }
;                 asm volatile("s_waitcnt lgkmcnt(0)" ::: "memory");
;                 float Tr[16];
;                 const int tb = ln >> 4, tl = ln & 15;
;                 const LAS float* NTl = NT + tb * (16 * 32 + 16); asm volatile("" : "+v"(NTl));
;                 f32x4 nvc[4], nvn[4];
; #pragma unroll
;                 for (int m = 0; m < 4; ++m) { nvc[m] = (f32x4){0.f, 0.f, 0.f, 0.f}; nvn[m] = nvc[m]; }
; #pragma unroll
;                 for (int cc = 0; cc < 16; ++cc) {
;                     const int cl = 15 - cc;
;                     if (cl >= 1) {
; #pragma unroll
;                         for (int m = 0; m < 4; ++m) if (4 * m + 3 > cl - 1) nvn[m] = *(const LAS f32x4*)(NTl + (cl - 1) * 32 + 4 * m);
;                     }
;                     float s0 = (cl == tl) ? 1.f : 0.f, s1 = 0.f, s2 = 0.f, s3 = 0.f;
; #pragma unroll
;                     for (int m = 0; m < 4; ++m) {
;                         if (4 * m + 3 > cl) {
;                             if (4 * m + 0 > cl) s0 -= Tr[4 * m + 0] * nvc[m][0];
;                             if (4 * m + 1 > cl) s1 -= Tr[4 * m + 1] * nvc[m][1];
;                             if (4 * m + 2 > cl) s2 -= Tr[4 * m + 2] * nvc[m][2];
;                             if (4 * m + 3 > cl) s3 -= Tr[4 * m + 3] * nvc[m][3];
;                         }
;                     }
;                     Tr[cl] = (s0 + s1) + (s2 + s3);
;                     asm volatile("" : "+v"(Tr[cl]) :: "memory");
; #pragma unroll
;                     for (int m = 0; m < 4; ++m) nvc[m] = nvn[m];
;                 }
.LBB0_271:
	s_andn2_b64 vcc, exec, s[78:79]
	s_mov_b32 s78, 0x800000
	s_mov_b32 s79, 0x3f317217
	s_mov_b32 s37, 0x7f800000
	s_movk_i32 s38, 0x5ff
	s_mov_b32 s40, 0xbfb8aa3b
	s_cbranch_vccnz .LBB0_283
	s_setprio 2
	v_readlane_b32 s0, v254, 30
	v_cmp_lt_i32_e32 vcc, v2, v189
	s_movk_i32 s22, 0x840
	v_lshl_add_u32 v119, v189, 2, s0
	v_cndmask_b32_e32 v121, 0, v68, vcc
	v_lshl_add_u32 v123, v188, 9, v119
	ds_write_b32 v123, v121
	v_or_b32_e32 v121, 1, v2
	v_cmp_lt_i32_e32 vcc, v121, v189
	v_lshl_add_u32 v121, v121, 7, v119
	v_xor_b32_e32 v68, 0x80000000, v68
	v_cndmask_b32_e32 v123, 0, v69, vcc
	v_cmp_lt_i32_e32 vcc, v117, v189
	ds_write_b32 v121, v123
	v_lshl_add_u32 v117, v117, 7, v119
	v_cndmask_b32_e32 v121, 0, v70, vcc
	v_cmp_lt_i32_e32 vcc, v116, v189
	ds_write_b32 v117, v121
	v_lshl_add_u32 v116, v116, 7, v119
	v_cndmask_b32_e32 v117, 0, v71, vcc
	v_cmp_lt_i32_e32 vcc, v115, v189
	ds_write_b32 v116, v117
	v_lshl_add_u32 v115, v115, 7, v119
	v_cndmask_b32_e32 v116, 0, v72, vcc
	v_cmp_lt_i32_e32 vcc, v113, v189
	ds_write_b32 v115, v116
	v_lshl_add_u32 v113, v113, 7, v119
	v_cndmask_b32_e32 v115, 0, v73, vcc
	v_cmp_lt_i32_e32 vcc, v109, v189
	ds_write_b32 v113, v115
	v_lshl_add_u32 v109, v109, 7, v119
	v_cndmask_b32_e32 v113, 0, v74, vcc
	v_cmp_lt_i32_e32 vcc, v3, v189
	ds_write_b32 v109, v113
	v_lshl_add_u32 v3, v3, 7, v119
	v_cndmask_b32_e32 v109, 0, v75, vcc
	v_cmp_lt_i32_e32 vcc, v111, v189
	ds_write_b32 v3, v109
	v_mov_b32_e32 v118, s0
	v_cndmask_b32_e32 v3, 0, v76, vcc
	v_lshl_add_u32 v76, v111, 7, v119
	v_cmp_lt_i32_e32 vcc, v106, v189
	ds_write_b32 v76, v3
	v_lshl_add_u32 v76, v106, 7, v119
	v_cndmask_b32_e32 v3, 0, v77, vcc
	v_cmp_lt_i32_e32 vcc, v110, v189
	ds_write_b32 v76, v3
	v_lshl_add_u32 v76, v110, 7, v119
	v_cndmask_b32_e32 v3, 0, v78, vcc
	v_cmp_lt_i32_e32 vcc, v104, v189
	ds_write_b32 v76, v3
	v_lshl_add_u32 v76, v104, 7, v119
	v_cndmask_b32_e32 v3, 0, v79, vcc
	v_cmp_lt_i32_e32 vcc, v114, v189
	ds_write_b32 v76, v3
	v_lshl_add_u32 v76, v114, 7, v119
	v_cndmask_b32_e32 v3, 0, v80, vcc
	v_cmp_lt_i32_e32 vcc, v112, v189
	ds_write_b32 v76, v3
	v_lshl_add_u32 v76, v112, 7, v119
	v_cndmask_b32_e32 v3, 0, v81, vcc
	v_cmp_lt_i32_e32 vcc, v107, v189
	ds_write_b32 v76, v3
	v_lshl_add_u32 v76, v107, 7, v119
	v_cndmask_b32_e32 v3, 0, v82, vcc
	v_cmp_lt_i32_e32 vcc, v105, v189
	ds_write_b32 v76, v3
	v_lshl_add_u32 v76, v105, 7, v119
	v_cndmask_b32_e32 v3, 0, v83, vcc
	ds_write_b32 v76, v3
	v_xor_b32_e32 v3, 0x80000000, v69
	v_cvt_pk_bf16_f32 v3, v68, v3
	v_cmp_gt_u32_e64 s[0:1], 16, v189
	v_xor_b32_e32 v69, 0x80000000, v71
	v_xor_b32_e32 v71, 0x80000000, v75
	v_cndmask_b32_e64 v68, v3, 0, s[0:1]
	v_xor_b32_e32 v3, 0x80000000, v70
	v_cvt_pk_bf16_f32 v3, v3, v69
	v_cndmask_b32_e64 v69, v3, 0, s[0:1]
	v_xor_b32_e32 v3, 0x80000000, v72
	v_xor_b32_e32 v70, 0x80000000, v73
	v_cvt_pk_bf16_f32 v3, v3, v70
	v_cndmask_b32_e64 v70, v3, 0, s[0:1]
	v_xor_b32_e32 v3, 0x80000000, v74
	v_mad_u32_u24 v2, v189, 40, v2
	v_cvt_pk_bf16_f32 v3, v3, v71
	v_lshl_add_u32 v2, v2, 1, 0
	v_cndmask_b32_e64 v71, v3, 0, s[0:1]
	v_add_u32_e32 v2, 0x1aa00, v2
	ds_write2_b64 v2, v[68:69], v[70:71] offset1:2
	v_lshrrev_b32_e32 v2, 4, v189
	v_mad_u32_u24 v109, v2, s22, v118
	v_and_b32_e32 v118, 15, v108
	s_waitcnt lgkmcnt(0)
	ds_read_b128 v[104:107], v109 offset:1840
	ds_read_b128 v[110:113], v109 offset:1712
	ds_read_b128 v[114:117], v109 offset:1584
	ds_read_b128 v[150:153], v109 offset:1456
	v_cmp_eq_u32_e64 s[22:23], 15, v118
	s_nop 1
	v_cndmask_b32_e64 v119, 0, 1.0, s[22:23]
	v_mov_b32_e32 v2, v119
	v_cmp_eq_u32_e64 s[22:23], 14, v118
	ds_read_b128 v[154:157], v109 offset:1312
	ds_read_b128 v[206:209], v109 offset:1328
	v_cndmask_b32_e64 v119, 0, 1.0, s[22:23]
	s_waitcnt lgkmcnt(5)
	v_fma_f32 v123, -v2, v107, 0
	v_add_f32_e32 v3, v123, v119
	v_cmp_eq_u32_e64 s[22:23], 13, v118
	ds_read_b128 v[222:225], v109 offset:1184
	ds_read_b128 v[226:229], v109 offset:1200
	s_waitcnt lgkmcnt(6)
	v_fma_f32 v123, -v2, v113, 0
	v_cndmask_b32_e64 v119, 0, 1.0, s[22:23]
	v_add_f32_e32 v119, v123, v119
	v_fma_f32 v121, -v3, v112, 0
	v_add_f32_e32 v71, v121, v119
	v_cmp_eq_u32_e64 s[22:23], 12, v118
	ds_read_b128 v[230:233], v109 offset:1056
	ds_read_b128 v[234:237], v109 offset:1072
	s_waitcnt lgkmcnt(7)
	v_fma_f32 v121, -v3, v116, 0
	v_fma_f32 v123, -v2, v117, 0
	v_cndmask_b32_e64 v119, 0, 1.0, s[22:23]
	v_add_f32_e32 v119, v121, v119
	v_add_f32_e32 v119, v123, v119
	v_fma_f32 v80, -v71, v115, 0
	v_add_f32_e32 v78, v80, v119
	v_cmp_eq_u32_e64 s[22:23], 11, v118
	ds_read_b128 v[238:241], v109 offset:928
	ds_read_b128 v[242:245], v109 offset:944
	s_waitcnt lgkmcnt(8)
	v_fma_f32 v80, -v71, v151, 0
	v_fma_f32 v121, -v3, v152, 0
	v_fma_f32 v123, -v2, v153, 0
	v_cndmask_b32_e64 v119, 0, 1.0, s[22:23]
	v_add_f32_e32 v119, v80, v119
	v_add_f32_e32 v119, v121, v119
	v_add_f32_e32 v119, v123, v119
	v_fma_f32 v75, -v78, v150, 0
	v_add_f32_e32 v77, v75, v119
	v_cmp_eq_u32_e64 s[22:23], 10, v118
	ds_read_b128 v[246:249], v109 offset:784
	ds_read_b128 v[104:107], v109 offset:800
	ds_read_b128 v[110:113], v109 offset:816
	s_waitcnt lgkmcnt(9)
	v_fma_f32 v75, -v78, v206, 0
	v_fma_f32 v80, -v71, v207, 0
	v_fma_f32 v121, -v3, v208, 0
	v_fma_f32 v123, -v2, v209, 0
	v_cndmask_b32_e64 v119, 0, 1.0, s[22:23]
	v_add_f32_e32 v119, v75, v119
	v_add_f32_e32 v119, v80, v119
	v_add_f32_e32 v119, v121, v119
	v_fma_f32 v123, -v77, v157, v123
	v_add_f32_e32 v79, v123, v119
	v_cmp_eq_u32_e64 s[22:23], 9, v118
	ds_read_b128 v[114:117], v109 offset:656
	ds_read_b128 v[150:153], v109 offset:672
	ds_read_b128 v[154:157], v109 offset:688
	s_waitcnt lgkmcnt(10)
; #define LAS __attribute__((address_space(3)))
; __device__ __forceinline__ void scan_pass1(const ScanP& sp, int b, int h, int seg, LAS unsigned char* lds) {
;     ...
; #pragma unroll
;                 for (int cc = 0; cc < 16; ++cc) {
;                     const int cl = 15 - cc;
;                     if (cl >= 1) {
; #pragma unroll
;                         for (int m = 0; m < 4; ++m) if (4 * m + 3 > cl - 1) nvn[m] = *(const LAS f32x4*)(NTl + (cl - 1) * 32 + 4 * m);
;                     }
;                     float s0 = (cl == tl) ? 1.f : 0.f, s1 = 0.f, s2 = 0.f, s3 = 0.f;
; #pragma unroll
;                     for (int m = 0; m < 4; ++m) {
;                         if (4 * m + 3 > cl) {
;                             if (4 * m + 0 > cl) s0 -= Tr[4 * m + 0] * nvc[m][0];
;                             if (4 * m + 1 > cl) s1 -= Tr[4 * m + 1] * nvc[m][1];
;                             if (4 * m + 2 > cl) s2 -= Tr[4 * m + 2] * nvc[m][2];
;                             if (4 * m + 3 > cl) s3 -= Tr[4 * m + 3] * nvc[m][3];
;                         }
;                     }
;                     Tr[cl] = (s0 + s1) + (s2 + s3);
;                     asm volatile("" : "+v"(Tr[cl]) :: "memory");
; #pragma unroll
;                     for (int m = 0; m < 4; ++m) nvc[m] = nvn[m];
;                 }
	v_fma_f32 v75, -v78, v226, 0
	v_fma_f32 v80, -v71, v227, 0
	v_fma_f32 v121, -v3, v228, 0
	v_fma_f32 v123, -v2, v229, 0
	v_fma_f32 v123, -v77, v225, v123
	v_cndmask_b32_e64 v119, 0, 1.0, s[22:23]
	v_add_f32_e32 v119, v75, v119
	v_add_f32_e32 v119, v80, v119
	v_add_f32_e32 v119, v123, v119
	v_fma_f32 v121, -v79, v224, v121
	v_add_f32_e32 v81, v121, v119
	v_cmp_eq_u32_e64 s[22:23], 8, v118
	ds_read_b128 v[206:209], v109 offset:528
	ds_read_b128 v[222:225], v109 offset:544
	ds_read_b128 v[226:229], v109 offset:560
	s_waitcnt lgkmcnt(11)
	v_fma_f32 v75, -v78, v234, 0
	v_fma_f32 v80, -v71, v235, 0
	v_fma_f32 v121, -v3, v236, 0
	v_fma_f32 v123, -v2, v237, 0
	v_fma_f32 v121, -v79, v232, v121
	v_fma_f32 v123, -v77, v233, v123
	v_cndmask_b32_e64 v119, 0, 1.0, s[22:23]
	v_add_f32_e32 v119, v75, v119
	v_add_f32_e32 v119, v121, v119
	v_add_f32_e32 v119, v123, v119
	v_fma_f32 v80, -v81, v231, v80
	v_add_f32_e32 v82, v80, v119
	v_cmp_eq_u32_e64 s[22:23], 7, v118
	s_waitcnt lgkmcnt(9)
	v_fma_f32 v75, -v78, v242, 0
	v_fma_f32 v80, -v71, v243, 0
	v_fma_f32 v121, -v3, v244, 0
	v_fma_f32 v123, -v2, v245, 0
	v_fma_f32 v80, -v81, v239, v80
	v_fma_f32 v121, -v79, v240, v121
	v_fma_f32 v123, -v77, v241, v123
	v_cndmask_b32_e64 v119, 0, 1.0, s[22:23]
	v_add_f32_e32 v119, v80, v119
	v_add_f32_e32 v119, v121, v119
	v_add_f32_e32 v119, v123, v119
	v_fma_f32 v75, -v82, v238, v75
	v_add_f32_e32 v76, v75, v119
	v_cmp_eq_u32_e64 s[22:23], 6, v118
	ds_read_b128 v[230:233], v109 offset:400
	ds_read_b128 v[234:237], v109 offset:416
	ds_read_b128 v[238:241], v109 offset:432
	s_waitcnt lgkmcnt(9)
	v_fma_f32 v75, -v78, v110, 0
	v_fma_f32 v80, -v71, v111, 0
	v_fma_f32 v121, -v3, v112, 0
	v_fma_f32 v123, -v2, v113, 0
	v_fma_f32 v75, -v82, v104, v75
	v_fma_f32 v80, -v81, v105, v80
	v_fma_f32 v121, -v79, v106, v121
	v_fma_f32 v123, -v77, v107, v123
	v_cndmask_b32_e64 v119, 0, 1.0, s[22:23]
	v_add_f32_e32 v119, v75, v119
	v_add_f32_e32 v119, v80, v119
	v_add_f32_e32 v119, v121, v119
	v_fma_f32 v123, -v76, v249, v123
	v_add_f32_e32 v83, v123, v119
	v_cmp_eq_u32_e64 s[22:23], 5, v118
	ds_read_b128 v[242:245], v109 offset:256
	ds_read_b128 v[246:249], v109 offset:272
	ds_read_b128 v[104:107], v109 offset:288
	ds_read_b128 v[110:113], v109 offset:304
	s_waitcnt lgkmcnt(10)
	v_fma_f32 v75, -v78, v154, 0
	v_fma_f32 v80, -v71, v155, 0
	v_fma_f32 v121, -v3, v156, 0
	v_fma_f32 v123, -v2, v157, 0
	v_fma_f32 v75, -v82, v150, v75
	v_fma_f32 v80, -v81, v151, v80
	v_fma_f32 v121, -v79, v152, v121
	v_fma_f32 v123, -v77, v153, v123
	v_fma_f32 v123, -v76, v117, v123
	v_cndmask_b32_e64 v119, 0, 1.0, s[22:23]
	v_add_f32_e32 v119, v75, v119
	v_add_f32_e32 v119, v80, v119
	v_add_f32_e32 v119, v123, v119
	v_fma_f32 v121, -v83, v116, v121
	v_add_f32_e32 v70, v121, v119
	v_cmp_eq_u32_e64 s[22:23], 4, v118
	s_waitcnt lgkmcnt(7)
	v_fma_f32 v75, -v78, v226, 0
	v_fma_f32 v80, -v71, v227, 0
	v_fma_f32 v121, -v3, v228, 0
	v_fma_f32 v123, -v2, v229, 0
	v_fma_f32 v75, -v82, v222, v75
	v_fma_f32 v80, -v81, v223, v80
	v_fma_f32 v121, -v79, v224, v121
	v_fma_f32 v123, -v77, v225, v123
	v_fma_f32 v121, -v83, v208, v121
	v_fma_f32 v123, -v76, v209, v123
	v_cndmask_b32_e64 v119, 0, 1.0, s[22:23]
	v_add_f32_e32 v119, v75, v119
	v_add_f32_e32 v119, v121, v119
	v_add_f32_e32 v119, v123, v119
	v_fma_f32 v80, -v70, v207, v80
	v_add_f32_e32 v74, v80, v119
	v_cmp_eq_u32_e64 s[22:23], 3, v118
	ds_read_b128 v[114:117], v109 offset:128
	ds_read_b128 v[150:153], v109 offset:144
	ds_read_b128 v[154:157], v109 offset:160
	ds_read_b128 v[206:209], v109 offset:176
	s_waitcnt lgkmcnt(8)
	v_fma_f32 v75, -v78, v238, 0
	v_fma_f32 v80, -v71, v239, 0
	v_fma_f32 v121, -v3, v240, 0
	v_fma_f32 v123, -v2, v241, 0
	v_fma_f32 v75, -v82, v234, v75
	v_fma_f32 v80, -v81, v235, v80
	v_fma_f32 v121, -v79, v236, v121
	v_fma_f32 v123, -v77, v237, v123
	v_fma_f32 v80, -v70, v231, v80
	v_fma_f32 v121, -v83, v232, v121
	v_fma_f32 v123, -v76, v233, v123
	v_cndmask_b32_e64 v119, 0, 1.0, s[22:23]
	v_add_f32_e32 v119, v80, v119
	v_add_f32_e32 v119, v121, v119
	v_add_f32_e32 v119, v123, v119
	v_fma_f32 v75, -v74, v230, v75
	v_add_f32_e32 v69, v75, v119
	v_cmp_eq_u32_e64 s[22:23], 2, v118
	ds_read_b128 v[222:225], v109 offset:0
	ds_read_b128 v[226:229], v109 offset:16
	ds_read_b128 v[230:233], v109 offset:32
	ds_read_b128 v[234:237], v109 offset:48
	s_waitcnt lgkmcnt(8)
	v_fma_f32 v75, -v78, v110, 0
	v_fma_f32 v80, -v71, v111, 0
	v_fma_f32 v121, -v3, v112, 0
	v_fma_f32 v123, -v2, v113, 0
	v_fma_f32 v75, -v82, v104, v75
	v_fma_f32 v80, -v81, v105, v80
	v_fma_f32 v121, -v79, v106, v121
	v_fma_f32 v123, -v77, v107, v123
	v_fma_f32 v75, -v74, v246, v75
	v_fma_f32 v80, -v70, v247, v80
	v_fma_f32 v121, -v83, v248, v121
	v_fma_f32 v123, -v76, v249, v123
	v_cndmask_b32_e64 v119, 0, 1.0, s[22:23]
	v_add_f32_e32 v119, v75, v119
	v_add_f32_e32 v119, v80, v119
	v_add_f32_e32 v119, v121, v119
	v_fma_f32 v123, -v69, v245, v123
	v_add_f32_e32 v73, v123, v119
	v_cmp_eq_u32_e64 s[22:23], 1, v118
	s_waitcnt lgkmcnt(4)
	v_fma_f32 v75, -v78, v206, 0
	v_fma_f32 v80, -v71, v207, 0
	v_fma_f32 v121, -v3, v208, 0
	v_fma_f32 v123, -v2, v209, 0
	v_fma_f32 v75, -v82, v154, v75
	v_fma_f32 v80, -v81, v155, v80
	v_fma_f32 v121, -v79, v156, v121
	v_fma_f32 v123, -v77, v157, v123
	v_fma_f32 v75, -v74, v150, v75
	v_fma_f32 v80, -v70, v151, v80
	v_fma_f32 v121, -v83, v152, v121
	v_fma_f32 v123, -v76, v153, v123
	v_fma_f32 v123, -v69, v117, v123
	v_cndmask_b32_e64 v119, 0, 1.0, s[22:23]
	v_add_f32_e32 v119, v75, v119
	v_add_f32_e32 v119, v80, v119
	v_add_f32_e32 v119, v123, v119
	v_fma_f32 v121, -v73, v116, v121
	v_add_f32_e32 v68, v121, v119
	v_cmp_eq_u32_e64 s[22:23], 0, v118
	s_waitcnt lgkmcnt(0)
	v_fma_f32 v75, -v78, v234, 0
	v_fma_f32 v80, -v71, v235, 0
	v_fma_f32 v121, -v3, v236, 0
	v_fma_f32 v123, -v2, v237, 0
	v_fma_f32 v75, -v82, v230, v75
	v_fma_f32 v80, -v81, v231, v80
	v_fma_f32 v121, -v79, v232, v121
	v_fma_f32 v123, -v77, v233, v123
	v_fma_f32 v75, -v74, v226, v75
	v_fma_f32 v80, -v70, v227, v80
	v_fma_f32 v121, -v83, v228, v121
	v_fma_f32 v123, -v76, v229, v123
	v_fma_f32 v121, -v73, v224, v121
	v_fma_f32 v123, -v69, v225, v123
	v_cndmask_b32_e64 v119, 0, 1.0, s[22:23]
	v_add_f32_e32 v119, v75, v119
	v_add_f32_e32 v119, v121, v119
	v_add_f32_e32 v119, v123, v119
	v_fma_f32 v80, -v68, v223, v80
	v_add_f32_e32 v72, v80, v119
	v_cmp_lt_u32_e32 vcc, 15, v189
	v_cmp_gt_u32_e64 s[22:23], 32, v108
	s_and_saveexec_b64 s[24:25], s[22:23]
	s_cbranch_execz .LBB0_282
; #define LAS __attribute__((address_space(3)))
; __device__ __forceinline__ unsigned pk2(float lo, float hi) { f32x2 v = {lo, hi}; bf16x2_t b = __builtin_convertvector(v, bf16x2_t); return __builtin_bit_cast(unsigned, b); }
; __device__ __forceinline__ void scan_pass1(const ScanP& sp, int b, int h, int seg, LAS unsigned char* lds) {
;     ...
;                 if (hh == 0) {
; #pragma unroll
;                     for (int q = 0; q < 4; ++q) {
;                         const bool mine = (q >> 1) == tb; const int o8 = 8 * (q & 1);
;                         u32x4 o; o.x = mine ? pk2(Tr[o8], Tr[o8 + 1]) : 0u; o.y = mine ? pk2(Tr[o8 + 2], Tr[o8 + 3]) : 0u; o.z = mine ? pk2(Tr[o8 + 4], Tr[o8 + 5]) : 0u; o.w = mine ? pk2(Tr[o8 + 6], Tr[o8 + 7]) : 0u;
;                         *(LAS u32x4*)(lds + O_TM + ln * 80 + 16 * q) = o;
;                     }
;                 }
	v_cvt_pk_bf16_f32 v68, v72, v68
	v_cvt_pk_bf16_f32 v69, v73, v69
	v_cvt_pk_bf16_f32 v70, v74, v70
	v_cndmask_b32_e64 v72, 0, v68, s[0:1]
	v_cndmask_b32_e64 v73, 0, v69, s[0:1]
	v_cndmask_b32_e64 v74, 0, v70, s[0:1]
	s_and_saveexec_b64 s[22:23], vcc
	s_xor_b64 s[22:23], exec, s[22:23]
	v_mov_b32_e32 v75, s93
	v_mov_b64_e32 v[106:107], v[74:75]
	v_mov_b64_e32 v[104:105], v[72:73]
	s_or_saveexec_b64 s[22:23], s[22:23]
	v_mov_b32_e32 v80, 0
	v_cvt_pk_bf16_f32 v75, v83, v76
	v_cvt_pk_bf16_f32 v76, v82, v81
	s_xor_b64 exec, exec, s[22:23]
	v_mov_b32_e32 v70, 0
	v_mov_b64_e32 v[106:107], v[74:75]
	v_cvt_pk_bf16_f32 v80, v82, v81
	v_mov_b32_e32 v69, v70
	v_mov_b32_e32 v68, v70
	v_mov_b64_e32 v[104:105], v[72:73]
	s_or_b64 exec, exec, s[22:23]
	s_movk_i32 s22, 0x50
	v_mad_u32_u24 v72, v189, s22, 0
	v_cvt_pk_bf16_f32 v77, v79, v77
	v_cvt_pk_bf16_f32 v78, v78, v71
	v_cvt_pk_bf16_f32 v79, v3, v2
	v_add_u32_e32 v72, 0x11800, v72
	v_cndmask_b32_e64 v81, 0, v77, s[0:1]
	v_cndmask_b32_e64 v82, 0, v78, s[0:1]
	v_cndmask_b32_e64 v83, 0, v79, s[0:1]
	v_mov_b32_e32 v71, s93
	ds_write_b128 v72, v[104:107]
	ds_write_b128 v72, v[80:83] offset:16
	s_and_saveexec_b64 s[0:1], vcc
	s_xor_b64 s[0:1], exec, s[0:1]
	v_mov_b32_e32 v71, v75
	s_andn2_saveexec_b64 s[0:1], s[0:1]
	v_mov_b32_e32 v79, 0
	v_mov_b32_e32 v78, v79
	v_mov_b32_e32 v77, v79
	v_mov_b32_e32 v76, v79
	s_or_b64 exec, exec, s[0:1]
	v_mul_u32_u24_e32 v2, 0x50, v189
	s_add_i32 s0, 0, 0x11800
	v_add_u32_e32 v2, s0, v2
	ds_write_b128 v2, v[68:71] offset:32
	ds_write_b128 v2, v[76:79] offset:48

; #define LAS __attribute__((address_space(3)))
; #define MFMA32(a, b, c) __builtin_amdgcn_mfma_f32_32x32x16_bf16((a), (b), (c), 0, 0, 0)
; __device__ __forceinline__ void scan_pass1(const ScanP& sp, int b, int h, int seg, LAS unsigned char* lds) {
;     ...
;         if (ci >= 0) {
;         __syncthreads();
;         if (w < 4) {
;             const bool isH = w < 2;
;             const int icol = 32 * (w & 1) + ln;
;             bf16x8 vfr[2];
;             if (isH) {
; #pragma unroll
;                 for (int ks = 0; ks < 2; ++ks) vfr[ks] = *(const LAS bf16x8*)(lds + O_VT + (icol * 40 + ks * 16 + hh * 8) * 2);
; #pragma unroll
;                 for (int ks = 0; ks < 2; ++ks) {
;                     P1 = MFMA32(*(const LAS bf16x8*)(lds + O_MK + (ln * 40 + ks * 16 + hh * 8) * 2), vfr[ks], P1);
;                     P2 = MFMA32(*(const LAS bf16x8*)(lds + O_NK + (ln * 40 + ks * 16 + hh * 8) * 2), vfr[ks], P2);
.LBB0_301:
	s_setprio 0
	s_andn2_b64 vcc, exec, s[88:89]
	s_waitcnt lgkmcnt(0)
	s_barrier
	s_cbranch_vccnz .LBB0_315
	s_mov_b64 s[0:1], -1
	s_andn2_b64 vcc, exec, s[62:63]
	v_mul_u32_u24_e32 v112, 0x50, v189
	v_lshlrev_b32_e32 v113, 4, v188
	s_cbranch_vccnz .LBB0_304
	v_mul_u32_u24_e32 v68, 0x50, v189
	v_lshlrev_b32_e32 v69, 4, v188
	s_mov_b64 s[0:1], 0
